# grid barrier: every waiting workgroup polls the top-level generation word directly (skips the per-XCD generation hop)
# speedup vs baseline: 1.0079x; 1.0064x over previous
; __device__ __forceinline__ unsigned xb_ld(unsigned* p)              { return __hip_atomic_load(p, __ATOMIC_RELAXED, __HIP_MEMORY_SCOPE_AGENT); }
; __device__ __forceinline__ unsigned xb_add(unsigned* p, unsigned v) { return __hip_atomic_fetch_add(p, v, __ATOMIC_RELAXED, __HIP_MEMORY_SCOPE_AGENT); }
; #define XB_SPIN(cond, bar) do { unsigned _sp = 0; while (cond) { __builtin_amdgcn_s_sleep(1); \
;     if ((++_sp & 255u) == 0u) { if (xb_ld(&(bar)[XB_TMO])) break; if (_sp > XB_SPIN_CAP) { atomicAdd(&(bar)[XB_TMO], 1u); break; } } } } while (0)
; __device__ __forceinline__ void xcd_barrier(const XcdBarrier& b) {
;     ...
;         const unsigned old = xb_add(&bar[XB_XSUB(b.x)], 1u);
;         const unsigned gen = old / nloc;
;         if (old + 1u == (gen + 1u) * nloc) {
;             __builtin_amdgcn_fence(__ATOMIC_RELEASE, "agent");
;             asm volatile("s_waitcnt vmcnt(0)" ::: "memory");
;             const unsigned og = xb_add(&bar[XB_TOP], 1u);
;             const unsigned tg = og / nx;
;             if (og + 1u == (tg + 1u) * nx) xb_add(&bar[XB_TOPGEN], 1u);
;             else XB_SPIN(xb_ld(&bar[XB_TOPGEN]) == tg, bar);
;             __builtin_amdgcn_fence(__ATOMIC_ACQUIRE, "agent");
;             xb_add(&bar[XB_XGEN(b.x)], 1u);
;             asm volatile("s_waitcnt vmcnt(0)" ::: "memory");
;         } else {
;             XB_SPIN(xb_ld(&bar[XB_XGEN(b.x)]) == gen, bar);
;             __builtin_amdgcn_fence(__ATOMIC_ACQUIRE, "agent");
;             asm volatile("s_waitcnt vmcnt(0)" ::: "memory");
;         }
.LBB0_64:
	s_or_b64 exec, exec, s[16:17]
	v_cvt_f32_u32_e32 v5, v3
	s_waitcnt vmcnt(0)
	v_readfirstlane_b32 s6, v4
	v_sub_u32_e32 v4, 0, v3
	v_rcp_iflag_f32_e32 v5, v5
	v_add_u32_e32 v6, s6, v2
	v_mul_f32_e32 v5, 0x4f7ffffe, v5
	v_cvt_u32_f32_e32 v5, v5
	v_mul_lo_u32 v2, v4, v5
	v_mul_hi_u32 v2, v5, v2
	v_add_u32_e32 v2, v5, v2
	v_mul_hi_u32 v2, v6, v2
	v_mul_lo_u32 v4, v2, v3
	v_sub_u32_e32 v4, v6, v4
	v_add_u32_e32 v5, 1, v2
	v_cmp_ge_u32_e32 vcc, v4, v3
	s_nop 1
	v_cndmask_b32_e32 v2, v2, v5, vcc
	v_sub_u32_e32 v5, v4, v3
	v_cndmask_b32_e32 v4, v4, v5, vcc
	v_add_u32_e32 v5, 1, v2
	v_cmp_ge_u32_e32 vcc, v4, v3
	v_add_u32_e32 v4, 1, v6
	s_nop 0
	v_cndmask_b32_e32 v2, v2, v5, vcc
	v_mul_lo_u32 v5, v3, v2
	v_add_u32_e32 v3, v5, v3
	v_cmp_ne_u32_e32 vcc, v4, v3
	s_and_saveexec_b64 s[6:7], vcc
	s_xor_b64 s[14:15], exec, s[6:7]
	s_cbranch_execz .LBB0_78
	s_waitcnt lgkmcnt(0)
	v_mov_b32_e32 v1, 0x3500
	global_load_dword v1, v1, s[48:49] sc1
	s_add_u32 s18, s48, 0x3500
	s_addc_u32 s19, s49, 0
	s_waitcnt vmcnt(0)
	v_cmp_eq_u32_e32 vcc, v1, v2
	s_and_saveexec_b64 s[16:17], vcc
	s_cbranch_execz .LBB0_77
	s_mov_b32 s6, 1
	s_mov_b64 s[20:21], 0
	v_mov_b32_e32 v1, 0
	s_branch .LBB0_68

; __device__ __forceinline__ unsigned xb_ld(unsigned* p)              { return __hip_atomic_load(p, __ATOMIC_RELAXED, __HIP_MEMORY_SCOPE_AGENT); }
; __device__ __forceinline__ unsigned xb_add(unsigned* p, unsigned v) { return __hip_atomic_fetch_add(p, v, __ATOMIC_RELAXED, __HIP_MEMORY_SCOPE_AGENT); }
; #define XB_SPIN(cond, bar) do { unsigned _sp = 0; while (cond) { __builtin_amdgcn_s_sleep(1); \
;     if ((++_sp & 255u) == 0u) { if (xb_ld(&(bar)[XB_TMO])) break; if (_sp > XB_SPIN_CAP) { atomicAdd(&(bar)[XB_TMO], 1u); break; } } } } while (0)
; __device__ __forceinline__ void xcd_barrier(const XcdBarrier& b) {
;     ...
;         const unsigned old = xb_add(&bar[XB_XSUB(b.x)], 1u);
;         const unsigned gen = old / nloc;
;         if (old + 1u == (gen + 1u) * nloc) {
;             __builtin_amdgcn_fence(__ATOMIC_RELEASE, "agent");
;             asm volatile("s_waitcnt vmcnt(0)" ::: "memory");
;             const unsigned og = xb_add(&bar[XB_TOP], 1u);
;             const unsigned tg = og / nx;
;             if (og + 1u == (tg + 1u) * nx) xb_add(&bar[XB_TOPGEN], 1u);
;             else XB_SPIN(xb_ld(&bar[XB_TOPGEN]) == tg, bar);
;             __builtin_amdgcn_fence(__ATOMIC_ACQUIRE, "agent");
;             xb_add(&bar[XB_XGEN(b.x)], 1u);
;             asm volatile("s_waitcnt vmcnt(0)" ::: "memory");
;         } else {
;             XB_SPIN(xb_ld(&bar[XB_XGEN(b.x)]) == gen, bar);
;             __builtin_amdgcn_fence(__ATOMIC_ACQUIRE, "agent");
;             asm volatile("s_waitcnt vmcnt(0)" ::: "memory");
;         }
.LBB0_183:
	s_or_b64 exec, exec, s[14:15]
	v_cvt_f32_u32_e32 v4, v2
	s_waitcnt vmcnt(0)
	v_readfirstlane_b32 s6, v3
	v_sub_u32_e32 v3, 0, v2
	v_rcp_iflag_f32_e32 v4, v4
	v_add_u32_e32 v5, s6, v1
	v_mul_f32_e32 v4, 0x4f7ffffe, v4
	v_cvt_u32_f32_e32 v4, v4
	v_mul_lo_u32 v1, v3, v4
	v_mul_hi_u32 v1, v4, v1
	v_add_u32_e32 v1, v4, v1
	v_mul_hi_u32 v1, v5, v1
	v_mul_lo_u32 v3, v1, v2
	v_sub_u32_e32 v3, v5, v3
	v_add_u32_e32 v4, 1, v1
	v_cmp_ge_u32_e32 vcc, v3, v2
	s_nop 1
	v_cndmask_b32_e32 v1, v1, v4, vcc
	v_sub_u32_e32 v4, v3, v2
	v_cndmask_b32_e32 v3, v3, v4, vcc
	v_add_u32_e32 v4, 1, v1
	v_cmp_ge_u32_e32 vcc, v3, v2
	v_add_u32_e32 v3, 1, v5
	s_nop 0
	v_cndmask_b32_e32 v1, v1, v4, vcc
	v_mul_lo_u32 v4, v2, v1
	v_add_u32_e32 v2, v4, v2
	v_cmp_ne_u32_e32 vcc, v3, v2
	s_and_saveexec_b64 s[6:7], vcc
	s_xor_b64 s[12:13], exec, s[6:7]
	s_cbranch_execz .LBB0_197
	s_waitcnt lgkmcnt(0)
	v_mov_b32_e32 v0, 0x3500
	global_load_dword v0, v0, s[48:49] sc1
	s_add_u32 s16, s48, 0x3500
	s_addc_u32 s17, s49, 0
	s_waitcnt vmcnt(0)
	v_cmp_eq_u32_e32 vcc, v0, v1
	s_and_saveexec_b64 s[14:15], vcc
	s_cbranch_execz .LBB0_196
	s_mov_b32 s6, 1
	s_mov_b64 s[18:19], 0
	v_mov_b32_e32 v0, 0
	s_branch .LBB0_187

; __device__ __forceinline__ unsigned xb_ld(unsigned* p)              { return __hip_atomic_load(p, __ATOMIC_RELAXED, __HIP_MEMORY_SCOPE_AGENT); }
; __device__ __forceinline__ unsigned xb_add(unsigned* p, unsigned v) { return __hip_atomic_fetch_add(p, v, __ATOMIC_RELAXED, __HIP_MEMORY_SCOPE_AGENT); }
; #define XB_SPIN(cond, bar) do { unsigned _sp = 0; while (cond) { __builtin_amdgcn_s_sleep(1); \
;     if ((++_sp & 255u) == 0u) { if (xb_ld(&(bar)[XB_TMO])) break; if (_sp > XB_SPIN_CAP) { atomicAdd(&(bar)[XB_TMO], 1u); break; } } } } while (0)
; __device__ __forceinline__ void xcd_barrier(const XcdBarrier& b) {
;     ...
;         const unsigned old = xb_add(&bar[XB_XSUB(b.x)], 1u);
;         const unsigned gen = old / nloc;
;         if (old + 1u == (gen + 1u) * nloc) {
;             __builtin_amdgcn_fence(__ATOMIC_RELEASE, "agent");
;             asm volatile("s_waitcnt vmcnt(0)" ::: "memory");
;             const unsigned og = xb_add(&bar[XB_TOP], 1u);
;             const unsigned tg = og / nx;
;             if (og + 1u == (tg + 1u) * nx) xb_add(&bar[XB_TOPGEN], 1u);
;             else XB_SPIN(xb_ld(&bar[XB_TOPGEN]) == tg, bar);
;             __builtin_amdgcn_fence(__ATOMIC_ACQUIRE, "agent");
;             xb_add(&bar[XB_XGEN(b.x)], 1u);
;             asm volatile("s_waitcnt vmcnt(0)" ::: "memory");
;         } else {
;             XB_SPIN(xb_ld(&bar[XB_XGEN(b.x)]) == gen, bar);
;             __builtin_amdgcn_fence(__ATOMIC_ACQUIRE, "agent");
;             asm volatile("s_waitcnt vmcnt(0)" ::: "memory");
;         }
.LBB0_561:
	s_or_b64 exec, exec, s[16:17]
	v_cvt_f32_u32_e32 v4, v2
	s_waitcnt vmcnt(0)
	v_readfirstlane_b32 s6, v3
	v_sub_u32_e32 v3, 0, v2
	v_rcp_iflag_f32_e32 v4, v4
	v_add_u32_e32 v5, s6, v1
	v_mul_f32_e32 v4, 0x4f7ffffe, v4
	v_cvt_u32_f32_e32 v4, v4
	v_mul_lo_u32 v1, v3, v4
	v_mul_hi_u32 v1, v4, v1
	v_add_u32_e32 v1, v4, v1
	v_mul_hi_u32 v1, v5, v1
	v_mul_lo_u32 v3, v1, v2
	v_sub_u32_e32 v3, v5, v3
	v_add_u32_e32 v4, 1, v1
	v_cmp_ge_u32_e32 vcc, v3, v2
	s_nop 1
	v_cndmask_b32_e32 v1, v1, v4, vcc
	v_sub_u32_e32 v4, v3, v2
	v_cndmask_b32_e32 v3, v3, v4, vcc
	v_add_u32_e32 v4, 1, v1
	v_cmp_ge_u32_e32 vcc, v3, v2
	v_add_u32_e32 v3, 1, v5
	s_nop 0
	v_cndmask_b32_e32 v1, v1, v4, vcc
	v_mul_lo_u32 v4, v2, v1
	v_add_u32_e32 v2, v4, v2
	v_cmp_ne_u32_e32 vcc, v3, v2
	s_and_saveexec_b64 s[6:7], vcc
	s_xor_b64 s[14:15], exec, s[6:7]
	s_cbranch_execz .LBB0_575
	s_waitcnt lgkmcnt(0)
	v_mov_b32_e32 v0, 0x3500
	global_load_dword v0, v0, s[48:49] sc1
	s_add_u32 s18, s48, 0x3500
	s_addc_u32 s19, s49, 0
	s_waitcnt vmcnt(0)
	v_cmp_eq_u32_e32 vcc, v0, v1
	s_and_saveexec_b64 s[16:17], vcc
	s_cbranch_execz .LBB0_574
	s_mov_b32 s6, 1
	s_mov_b64 s[20:21], 0
	v_mov_b32_e32 v0, 0
	s_branch .LBB0_565

; __device__ __forceinline__ unsigned xb_ld(unsigned* p)              { return __hip_atomic_load(p, __ATOMIC_RELAXED, __HIP_MEMORY_SCOPE_AGENT); }
; __device__ __forceinline__ unsigned xb_add(unsigned* p, unsigned v) { return __hip_atomic_fetch_add(p, v, __ATOMIC_RELAXED, __HIP_MEMORY_SCOPE_AGENT); }
; #define XB_SPIN(cond, bar) do { unsigned _sp = 0; while (cond) { __builtin_amdgcn_s_sleep(1); \
;     if ((++_sp & 255u) == 0u) { if (xb_ld(&(bar)[XB_TMO])) break; if (_sp > XB_SPIN_CAP) { atomicAdd(&(bar)[XB_TMO], 1u); break; } } } } while (0)
; __device__ __forceinline__ void xcd_barrier(const XcdBarrier& b) {
;     ...
;         const unsigned old = xb_add(&bar[XB_XSUB(b.x)], 1u);
;         const unsigned gen = old / nloc;
;         if (old + 1u == (gen + 1u) * nloc) {
;             __builtin_amdgcn_fence(__ATOMIC_RELEASE, "agent");
;             asm volatile("s_waitcnt vmcnt(0)" ::: "memory");
;             const unsigned og = xb_add(&bar[XB_TOP], 1u);
;             const unsigned tg = og / nx;
;             if (og + 1u == (tg + 1u) * nx) xb_add(&bar[XB_TOPGEN], 1u);
;             else XB_SPIN(xb_ld(&bar[XB_TOPGEN]) == tg, bar);
;             __builtin_amdgcn_fence(__ATOMIC_ACQUIRE, "agent");
;             xb_add(&bar[XB_XGEN(b.x)], 1u);
;             asm volatile("s_waitcnt vmcnt(0)" ::: "memory");
;         } else {
;             XB_SPIN(xb_ld(&bar[XB_XGEN(b.x)]) == gen, bar);
;             __builtin_amdgcn_fence(__ATOMIC_ACQUIRE, "agent");
;             asm volatile("s_waitcnt vmcnt(0)" ::: "memory");
;         }
.LBB0_2049:
	s_or_b64 exec, exec, s[12:13]
	v_cvt_f32_u32_e32 v4, v2
	s_waitcnt vmcnt(0)
	v_readfirstlane_b32 s10, v3
	v_sub_u32_e32 v3, 0, v2
	v_rcp_iflag_f32_e32 v4, v4
	v_add_u32_e32 v5, s10, v1
	v_mul_f32_e32 v4, 0x4f7ffffe, v4
	v_cvt_u32_f32_e32 v4, v4
	v_mul_lo_u32 v1, v3, v4
	v_mul_hi_u32 v1, v4, v1
	v_add_u32_e32 v1, v4, v1
	v_mul_hi_u32 v1, v5, v1
	v_mul_lo_u32 v3, v1, v2
	v_sub_u32_e32 v3, v5, v3
	v_add_u32_e32 v4, 1, v1
	v_cmp_ge_u32_e32 vcc, v3, v2
	s_nop 1
	v_cndmask_b32_e32 v1, v1, v4, vcc
	v_sub_u32_e32 v4, v3, v2
	v_cndmask_b32_e32 v3, v3, v4, vcc
	v_add_u32_e32 v4, 1, v1
	v_cmp_ge_u32_e32 vcc, v3, v2
	v_add_u32_e32 v3, 1, v5
	s_nop 0
	v_cndmask_b32_e32 v1, v1, v4, vcc
	v_mul_lo_u32 v4, v2, v1
	v_add_u32_e32 v2, v4, v2
	v_cmp_ne_u32_e32 vcc, v3, v2
	s_and_saveexec_b64 s[10:11], vcc
	s_xor_b64 s[10:11], exec, s[10:11]
	s_cbranch_execz .LBB0_2063
	s_waitcnt lgkmcnt(0)
	v_mov_b32_e32 v0, 0x3500
	global_load_dword v0, v0, s[48:49] sc1
	s_add_u32 s14, s48, 0x3500
	s_addc_u32 s15, s49, 0
	s_waitcnt vmcnt(0)
	v_cmp_eq_u32_e32 vcc, v0, v1
	s_and_saveexec_b64 s[12:13], vcc
	s_cbranch_execz .LBB0_2062
	s_mov_b32 s26, 1
	s_mov_b64 s[16:17], 0
	v_mov_b32_e32 v0, 0
	s_branch .LBB0_2053

; __device__ __forceinline__ unsigned xb_ld(unsigned* p)              { return __hip_atomic_load(p, __ATOMIC_RELAXED, __HIP_MEMORY_SCOPE_AGENT); }
; __device__ __forceinline__ unsigned xb_add(unsigned* p, unsigned v) { return __hip_atomic_fetch_add(p, v, __ATOMIC_RELAXED, __HIP_MEMORY_SCOPE_AGENT); }
; #define XB_SPIN(cond, bar) do { unsigned _sp = 0; while (cond) { __builtin_amdgcn_s_sleep(1); \
;     if ((++_sp & 255u) == 0u) { if (xb_ld(&(bar)[XB_TMO])) break; if (_sp > XB_SPIN_CAP) { atomicAdd(&(bar)[XB_TMO], 1u); break; } } } } while (0)
; __device__ __forceinline__ void xcd_barrier(const XcdBarrier& b) {
;     ...
;         const unsigned old = xb_add(&bar[XB_XSUB(b.x)], 1u);
;         const unsigned gen = old / nloc;
;         if (old + 1u == (gen + 1u) * nloc) {
;             __builtin_amdgcn_fence(__ATOMIC_RELEASE, "agent");
;             asm volatile("s_waitcnt vmcnt(0)" ::: "memory");
;             const unsigned og = xb_add(&bar[XB_TOP], 1u);
;             const unsigned tg = og / nx;
;             if (og + 1u == (tg + 1u) * nx) xb_add(&bar[XB_TOPGEN], 1u);
;             else XB_SPIN(xb_ld(&bar[XB_TOPGEN]) == tg, bar);
;             __builtin_amdgcn_fence(__ATOMIC_ACQUIRE, "agent");
;             xb_add(&bar[XB_XGEN(b.x)], 1u);
;             asm volatile("s_waitcnt vmcnt(0)" ::: "memory");
;         } else {
;             XB_SPIN(xb_ld(&bar[XB_XGEN(b.x)]) == gen, bar);
;             __builtin_amdgcn_fence(__ATOMIC_ACQUIRE, "agent");
;             asm volatile("s_waitcnt vmcnt(0)" ::: "memory");
;         }
.LBB0_2285:
	s_or_b64 exec, exec, s[10:11]
	v_cvt_f32_u32_e32 v4, v2
	s_waitcnt vmcnt(0)
	v_readfirstlane_b32 s3, v3
	v_sub_u32_e32 v3, 0, v2
	v_rcp_iflag_f32_e32 v4, v4
	v_add_u32_e32 v5, s3, v1
	v_mul_f32_e32 v4, 0x4f7ffffe, v4
	v_cvt_u32_f32_e32 v4, v4
	v_mul_lo_u32 v1, v3, v4
	v_mul_hi_u32 v1, v4, v1
	v_add_u32_e32 v1, v4, v1
	v_mul_hi_u32 v1, v5, v1
	v_mul_lo_u32 v3, v1, v2
	v_sub_u32_e32 v3, v5, v3
	v_add_u32_e32 v4, 1, v1
	v_cmp_ge_u32_e32 vcc, v3, v2
	s_nop 1
	v_cndmask_b32_e32 v1, v1, v4, vcc
	v_sub_u32_e32 v4, v3, v2
	v_cndmask_b32_e32 v3, v3, v4, vcc
	v_add_u32_e32 v4, 1, v1
	v_cmp_ge_u32_e32 vcc, v3, v2
	v_add_u32_e32 v3, 1, v5
	s_nop 0
	v_cndmask_b32_e32 v1, v1, v4, vcc
	v_mul_lo_u32 v4, v2, v1
	v_add_u32_e32 v2, v4, v2
	v_cmp_ne_u32_e32 vcc, v3, v2
	s_and_saveexec_b64 s[8:9], vcc
	s_xor_b64 s[8:9], exec, s[8:9]
	s_cbranch_execz .LBB0_2299
	s_waitcnt lgkmcnt(0)
	v_mov_b32_e32 v0, 0x3500
	global_load_dword v0, v0, s[48:49] sc1
	s_add_u32 s12, s48, 0x3500
	s_addc_u32 s13, s49, 0
	s_waitcnt vmcnt(0)
	v_cmp_eq_u32_e32 vcc, v0, v1
	s_and_saveexec_b64 s[10:11], vcc
	s_cbranch_execz .LBB0_2298
	s_mov_b32 s3, 1
	s_mov_b64 s[14:15], 0
	v_mov_b32_e32 v0, 0
	s_branch .LBB0_2289
